# P1 and P8 prompt GEMMs on 208 XCD-aligned WGs (7 rounds), 48/40 other WGs copy cache chunks (q22) beside them
# speedup vs baseline: 1.0221x; 1.0075x over previous
; #define PG8_LAS __attribute__((address_space(3)))
; #define PG8_STAGE(bufoff, gbase, voff) do { _Pragma("unroll") for (int _i = 0; _i < 2; ++_i) \
;         __builtin_amdgcn_global_load_lds((const unsigned*)((const char*)(gbase) + (voff)[_i]), (PG8_LAS unsigned*)(lds + (bufoff) + ldsw + _i * 8192), 16, 0, 0); } while (0)
; #define PG8_BAR __builtin_amdgcn_s_barrier()
; template <class Epi, class Sched, bool ALIGN_EPI = false, bool SP2 = false>
; __device__ __forceinline__ void gemm_phase(PG8_LAS unsigned char* lds, const Gemm g, const Sched& S, const Epi& E) {
;     int tid_o = threadIdx.x; asm volatile("" : "+v"(tid_o));
;     const int tid = tid_o, wid = __builtin_amdgcn_readfirstlane(tid >> 6), lane = tid & 63, wr = wid >> 2, wc = wid & 3, fr = lane & 15, fq = lane >> 4;
;     const int K = g.K, nt = K / BK;
;     unsigned voffA[2], voffB[2];
; #pragma unroll
;     for (int i = 0; i < 2; ++i) { int R, C; stage_rc(tid * 16 + i * 8192, R, C); const int Rb = Epi::PERM ? ((R & ~31) + perm32(R & 31)) : R;
;         voffA[i] = (unsigned)(R * K + C) * 2u; voffB[i] = (unsigned)(Rb * K + C) * 2u; }
;     const size_t kstep = (size_t)(BK * 2);
;     const size_t hstep = (size_t)HALF * K * 2;
;     const size_t tstep = 2 * hstep;
;     const unsigned ldsw = (unsigned)wid * 1024u;
;     const int aoff = lds_byte(wr * 64 + fr, fq * 8), boff = lds_byte(wc * 32 + fr, fq * 8);
;     ...
;     Unit cur, nxt; int ui = 0;
;     if (!S.next(0, cur)) return;
;     f32x4 acc[2][2][4][2];
; #pragma unroll
;     for (int a = 0; a < 2; ++a)
; #pragma unroll
;         for (int b = 0; b < 2; ++b)
; #pragma unroll
;             for (int m = 0; m < 4; ++m)
; #pragma unroll
;                 for (int n = 0; n < 2; ++n) acc[a][b][m][n] = (f32x4){0.f, 0.f, 0.f, 0.f};
;     bf16x8 At[4][2], B0[2][2], B1[2][2];
;     const char* cA = (const char*)g.A + (size_t)cur.pm * tstep; const char* cB = (const char*)g.Bt + (size_t)cur.pn * tstep;
;     S.a_ready(cur);
;     if constexpr (SP2) {
;         PG8_STAGE(PG8_SB(0, 0), cB, voffB); PG8_STAGE(PG8_SB(0, 1), cB + hstep, voffB); PG8_STAGE(PG8_SA(0, 0), cA, voffA); PG8_STAGE(PG8_SA(0, 1), cA + hstep, voffA);
;         if (wr == 1) PG8_BAR;
; __global__ void __launch_bounds__(512, 2) mk_fwd(Args args) {
;     ...
;     if (IN(8)) {
;         { pg8::EpiSwiGLU E{rss2, ACT}; GEMM(pg8::EpiSwiGLU, X2B, W6, 2 * FF, D, 64, 0, G - 8, bid < G - 8 ? bid : -1, E); }
.LBB0_1479:
	s_cmp_lt_i32 s82, 9
	s_cselect_b64 s[0:1], -1, 0
	s_add_u32 s48, s80, 0x1efb100
	s_addc_u32 s49, s81, 0
	s_and_b64 s[0:1], s[0:1], s[2:3]
	s_andn2_b64 vcc, exec, s[0:1]
	s_cbranch_vccnz .LBB0_1560
	s_add_i32 s33, s68, -48
	s_cmp_ge_i32 s96, s33
	s_cselect_b64 s[2:3], -1, 0
	s_cmp_lt_i32 s96, s33
	s_cselect_b32 s42, s96, -1
	s_cmp_gt_i32 s42, -1
	s_cselect_b64 s[4:5], -1, 0
	s_cmp_lt_i32 s42, s33
	s_cselect_b64 s[6:7], -1, 0
	s_and_b64 s[6:7], s[4:5], s[6:7]
	s_and_b64 s[6:7], s[6:7], exec
	s_cselect_b32 s6, 0x580, 0
	s_cmp_lt_u32 s42, s6
	s_cselect_b64 s[20:21], -1, 0
	s_waitcnt vmcnt(0)
	v_mov_b32_e32 v11, v0
	s_and_b64 s[4:5], s[4:5], s[20:21]
	s_andn2_b64 vcc, exec, s[4:5]
	v_readfirstlane_b32 s4, v11
	s_cbranch_vccnz .LBB0_1496
	v_lshlrev_b32_e32 v1, 4, v11
	v_add_u32_e32 v2, 0x2000, v1
	s_waitcnt lgkmcnt(0)
	v_ashrrev_i32_e32 v3, 31, v2
	v_lshrrev_b32_e32 v3, 22, v3
	v_add_u32_e32 v3, v2, v3
	v_ashrrev_i32_e32 v10, 10, v3
	v_mul_i32_i24_e32 v4, 0x400, v10
	v_sub_u32_e32 v2, v2, v4
	v_lshrrev_b32_e32 v4, 4, v2
	v_bitop3_b32 v2, v4, v2, 32 bitop3:0x6c
	v_ashrrev_i32_e32 v4, 31, v2
	v_lshrrev_b32_e32 v4, 26, v4
	v_add_u32_e32 v4, v2, v4
	v_ashrrev_i32_e32 v12, 6, v4
	v_and_b32_e32 v4, 0xc0, v4
	v_sub_u32_e32 v2, v2, v4
	v_mov_b32_e32 v4, 1
	v_lshlrev_b32_e32 v3, 5, v10
	v_ashrrev_i16_sdwa v2, v4, sext(v2) dst_sel:DWORD dst_unused:UNUSED_PAD src0_sel:DWORD src1_sel:BYTE_0
	v_and_b32_e32 v3, 32, v3
	v_bfe_i32 v13, v2, 0, 16
	v_add_u32_e32 v2, v3, v13
	v_lshlrev_b32_e32 v3, 3, v10
	v_and_b32_e32 v3, 0x1ffff0, v3
	v_add_lshl_u32 v3, v12, v3, 11
	v_lshl_add_u32 v130, v2, 1, v3
	v_bfe_i32 v3, v11, 27, 1
	v_lshrrev_b32_e32 v3, 22, v3
	v_add_u32_e32 v3, v1, v3
	v_and_b32_e32 v3, 0xfffffc00, v3
	s_lshr_b32 s44, s6, 3
	s_and_b32 s20, s42, 7
	v_sub_u32_e32 v1, v1, v3
	s_lshr_b32 s21, s42, 3
	s_mul_i32 s20, s44, s20
	v_lshrrev_b32_e32 v3, 4, v1
	s_add_i32 s20, s20, s21
	v_bitop3_b32 v1, v3, v1, 32 bitop3:0x6c
	s_and_b32 s21, s20, 0xffff
	v_ashrrev_i32_e32 v3, 31, v1
	s_mul_i32 s21, s21, 0xba2f
	v_ashrrev_i32_e32 v2, 31, v11
	v_lshrrev_b32_e32 v3, 26, v3
	s_lshr_b32 s21, s21, 23
	v_lshrrev_b32_e32 v2, 26, v2
	v_add_u32_e32 v3, v1, v3
	s_lshl_b32 s22, s21, 3
	s_mulk_i32 s21, 0xb0
	v_add_u32_e32 v2, v11, v2
	v_ashrrev_i32_e32 v15, 6, v3
	v_and_b32_e32 v3, 0xc0, v3
	s_sub_i32 s20, s20, s21
	v_ashrrev_i32_e32 v14, 6, v2
	v_sub_u32_e32 v1, v1, v3
	s_and_b32 s21, s20, 7
	v_lshlrev_b32_e32 v2, 5, v14
	v_ashrrev_i16_sdwa v1, v4, sext(v1) dst_sel:DWORD dst_unused:UNUSED_PAD src0_sel:DWORD src1_sel:BYTE_0
	s_or_b32 s21, s21, s22
	s_ashr_i32 s7, s4, 6
	v_and_b32_e32 v2, 32, v2
	v_bfe_i32 v16, v1, 0, 16
	s_and_b32 s62, s21, 0xfff
	s_bfe_u32 s22, s20, 0x50003
	s_ashr_i32 s5, s4, 8
	s_lshl_b32 s43, s7, 10
	v_add_u32_e32 v1, v2, v16
	v_lshlrev_b32_e32 v2, 3, v14
	s_lshl_b32 s23, s62, 19
	s_lshl_b32 s20, s22, 19
	v_and_b32_e32 v2, 0x1ffff0, v2
	s_add_u32 s38, s48, s20
	v_add_lshl_u32 v2, v15, v2, 11
	s_addc_u32 s39, s49, 0
	s_add_i32 s45, s43, 0
	v_lshl_add_u32 v132, v1, 1, v2
	s_add_i32 m0, s45, 0x10000
	v_mov_b32_e32 v133, 0
	global_load_lds_dwordx4 v132, s[38:39]
	s_add_i32 m0, s45, 0x12000
	s_add_u32 s20, s38, 0x40000
	global_load_lds_dwordx4 v130, s[38:39]
	s_addc_u32 s21, s39, 0
	s_add_i32 m0, s45, 0x14000
	v_mov_b32_e32 v131, v133
	global_load_lds_dwordx4 v132, s[20:21]
	s_add_i32 m0, s45, 0x16000
	s_add_u32 s36, s12, s23
	s_addc_u32 s37, s13, 0
	s_add_i32 s46, s45, 0x2000
	global_load_lds_dwordx4 v130, s[20:21]
	s_mov_b32 m0, s45
	s_add_u32 s20, s36, 0x40000
	global_load_lds_dwordx4 v132, s[36:37]
	s_mov_b32 m0, s46
	s_addc_u32 s21, s37, 0
	s_add_i32 s47, s45, 0x4000
	global_load_lds_dwordx4 v130, s[36:37]
	s_mov_b32 m0, s47
	s_add_i32 s56, s45, 0x6000
	global_load_lds_dwordx4 v132, s[20:21]
	s_mov_b32 m0, s56
	s_cmp_eq_u32 s5, 1
	global_load_lds_dwordx4 v130, s[20:21]
	v_lshl_add_u64 v[8:9], s[38:39], 0, v[132:133]
	v_lshl_add_u64 v[6:7], s[38:39], 0, v[130:131]
	v_lshl_add_u64 v[2:3], s[36:37], 0, v[132:133]
	s_cselect_b64 s[20:21], -1, 0
	s_cmp_lg_u32 s5, 1
	v_lshl_add_u64 v[4:5], s[36:37], 0, v[130:131]
	s_cbranch_scc1 .LBB0_1483
	s_barrier

; #define GEMM(EPI, Aop, Bop, Nn, Kk, nM_, pmoff, Gs, cs, Eobj) do { pg8::Gemm g_{Aop, Bop, T, Nn, Kk}; pg8::SubOrder S_; S_.init(nM_, (Nn) / 256, pmoff, Gs, cs); \
;         pg8::gemm_phase<EPI, pg8::SubOrder, true, true>(lds, g_, S_, Eobj); } while (0)
; __device__ __forceinline__ ChunkD chunk_desc(const Args& a, int id) {
;     const float* src; float* dst; int nrows;
;     if (id < 5376) {
;         int g, r;
;         if (id < 256) { g = 0; r = id; } else if (id < 1280) { g = 1; r = id - 256; } else { g = 2; r = id - 1280; }
;         const int W = 128 << (2 * g), cpb = 1 << (2 * g);
;         const int kv = r / (128 * cpb), r2 = r % (128 * cpb), b = r2 / cpb, ch = r2 % cpb, row0 = ch * 128;
;         nrows = (W - 4 - row0) < 128 ? (W - 4 - row0) : 128;
;         size_t oks = O_KS0; for (int gg = 0; gg < g; ++gg) oks += (size_t)2 * 128 * (128 << (2 * gg)) * 256;
;         oks += (size_t)kv * 128 * W * 256;
;         src = a.in[2 + 2 * g + kv] + ((size_t)b * W + 4 + row0) * 256; dst = a.out + oks + ((size_t)b * W + row0) * 256;
;     } else { const int b = id - 5376; src = a.in[8] + ((size_t)b * 30 + 4) * 512; dst = a.out + O_CS + (size_t)b * 30 * 512; nrows = 52; }
;     ChunkD d; d.s4 = (const f32x4*)src; d.d4 = (f32x4*)dst; d.n4 = nrows * 64; return d;
; }
; __global__ void __launch_bounds__(512, 2) mk_fwd(Args args) {
;     ...
;         { pg8::EpiSwiGLU E{rss2, ACT}; GEMM(pg8::EpiSwiGLU, X2B, W6, 2 * FF, D, 64, 0, G - 8, bid < G - 8 ? bid : -1, E); }
;         if (bid >= G - 8) { const int sb = bid - (G - 8);
.LBB0_1496:
	s_add_i32 s33, s68, -8
	s_cmp_ge_i32 s96, s33
	s_cselect_b64 s[2:3], -1, 0
	s_cbranch_scc1 .Lp8_chain
	s_add_i32 s98, s68, -48
	s_cmp_lt_i32 s96, s98
	s_cbranch_scc1 .LBB0_1560
	s_movk_i32 s99, 22
	s_load_dwordx8 s[16:23], s[90:91], 0x10
	s_load_dwordx4 s[24:27], s[90:91], 0x30
	s_load_dwordx2 s[28:29], s[90:91], 0x40
	s_load_dwordx2 s[30:31], s[90:91], 0xd8
	s_add_u32 s14, s80, 0x4000
	s_addc_u32 s15, s81, 0
	v_and_b32_e32 v66, 63, v0
	v_lshlrev_b32_e32 v66, 4, v66
	v_readfirstlane_b32 s34, v0
	s_lshr_b32 s34, s34, 6
	s_lshl_b32 s34, s34, 10
	v_cmp_eq_u32_e32 vcc, 0, v0
	s_and_saveexec_b64 s[46:47], vcc
	s_cbranch_execz .Lfc8_noatom
	v_mov_b32_e32 v67, 0
	v_mov_b32_e32 v68, s99
	global_atomic_add v68, v67, v68, s[14:15] sc0
	v_mov_b32_e32 v67, 0x20070
	s_waitcnt vmcnt(0)
	ds_write_b32 v67, v68
.Lfc8_noatom:
	s_or_b64 exec, exec, s[46:47]
	s_waitcnt lgkmcnt(0)
	s_barrier
	v_mov_b32_e32 v67, 0x20070
	ds_read_b32 v68, v67
	s_waitcnt lgkmcnt(0)
	s_nop 0
	v_readfirstlane_b32 s2, v68
	s_add_u32 s3, s2, s99
	s_min_u32 s3, s3, 0x1580
.Lfc8_loop:
	s_cmp_ge_u32 s2, s3
	s_cbranch_scc1 .Lfc8_done
	s_cmpk_lt_u32 s2, 0x1500
	s_cbranch_scc0 .Lfc8_conv
	s_lshl_b32 s100, s2, 17
	s_add_u32 s6, s30, s100
	s_addc_u32 s7, s31, 0
	s_add_u32 s6, s6, 0x573c000
	s_addc_u32 s7, s7, 0
	s_cmpk_lt_u32 s2, 0x100
	s_cbranch_scc1 .Lfc8_g0
	s_cmpk_lt_u32 s2, 0x500
	s_cbranch_scc1 .Lfc8_g1
	s_sub_u32 s100, s2, 0x500
	s_and_b32 s101, s100, 15
	s_cmp_eq_u32 s101, 15
	s_mov_b32 s33, 0x1fc00
	s_cselect_b32 s33, 0x1ec00, s33
	s_bitcmp1_b32 s100, 11
	s_cselect_b64 s[4:5], s[26:27], s[24:25]
	s_and_b32 s100, s100, 0x7ff
	s_branch .Lfc8_src
.Lfc8_g1:
	s_sub_u32 s100, s2, 0x100
	s_and_b32 s101, s100, 3
	s_cmp_eq_u32 s101, 3
	s_mov_b32 s33, 0x1fc00
	s_cselect_b32 s33, 0x1ec00, s33
	s_bitcmp1_b32 s100, 9
	s_cselect_b64 s[4:5], s[22:23], s[20:21]
	s_and_b32 s100, s100, 0x1ff
	s_branch .Lfc8_src
.Lfc8_g0:
	s_mov_b32 s33, 0x1ec00
	s_bitcmp1_b32 s2, 7
	s_cselect_b64 s[4:5], s[18:19], s[16:17]
	s_and_b32 s100, s2, 0x7f
.Lfc8_src:
	s_lshl_b32 s100, s100, 17
	s_add_u32 s4, s4, s100
	s_addc_u32 s5, s5, 0
	s_add_u32 s4, s4, 0x1000
	s_addc_u32 s5, s5, 0
	s_branch .Lfc8_copy
.Lfc8_conv:
	s_sub_u32 s100, s2, 0x1500
	s_mul_i32 s100, s100, 0xf000
	s_add_u32 s4, s28, s100
	s_addc_u32 s5, s29, 0
	s_add_u32 s4, s4, 0x2000
	s_addc_u32 s5, s5, 0
	s_add_u32 s6, s30, s100
	s_addc_u32 s7, s31, 0
	s_add_u32 s6, s6, 0x2f73c000
	s_addc_u32 s7, s7, 0
	s_mov_b32 s33, 0xcc00
; __device__ __forceinline__ void copy_chunk(const Args& a, int id, int tid) {
;     const ChunkD c0 = chunk_desc(a, id);
;     f32x4 v0[16];
; #pragma unroll
;     for (int k = 0; k < 16; ++k) { const int i = tid + 512 * k; if (i < c0.n4) v0[k] = __builtin_nontemporal_load(c0.s4 + i); }
; #pragma unroll
;     for (int k = 0; k < 16; ++k) { const int i = tid + 512 * k; if (i < c0.n4) __builtin_nontemporal_store(v0[k], c0.d4 + i); }
; }
.Lfc8_copy:
	s_min_u32 s35, s34, s33
	s_add_u32 s36, s4, s35
	s_addc_u32 s37, s5, 0
	global_load_dwordx4 v[2:5], v66, s[36:37] nt
	s_add_u32 s35, s34, 0x2000
	s_min_u32 s35, s35, s33
	s_add_u32 s38, s4, s35
	s_addc_u32 s39, s5, 0
	global_load_dwordx4 v[6:9], v66, s[38:39] nt
	s_add_u32 s35, s34, 0x4000
	s_min_u32 s35, s35, s33
	s_add_u32 s36, s4, s35
	s_addc_u32 s37, s5, 0
	global_load_dwordx4 v[10:13], v66, s[36:37] nt
	s_add_u32 s35, s34, 0x6000
	s_min_u32 s35, s35, s33
	s_add_u32 s38, s4, s35
	s_addc_u32 s39, s5, 0
	global_load_dwordx4 v[14:17], v66, s[38:39] nt
	s_add_u32 s35, s34, 0x8000
	s_min_u32 s35, s35, s33
	s_add_u32 s36, s4, s35
	s_addc_u32 s37, s5, 0
	global_load_dwordx4 v[18:21], v66, s[36:37] nt
	s_add_u32 s35, s34, 0xa000
	s_min_u32 s35, s35, s33
	s_add_u32 s38, s4, s35
	s_addc_u32 s39, s5, 0
	global_load_dwordx4 v[22:25], v66, s[38:39] nt
	s_add_u32 s35, s34, 0xc000
	s_min_u32 s35, s35, s33
	s_add_u32 s36, s4, s35
	s_addc_u32 s37, s5, 0
	global_load_dwordx4 v[26:29], v66, s[36:37] nt
	s_add_u32 s35, s34, 0xe000
	s_min_u32 s35, s35, s33
	s_add_u32 s38, s4, s35
	s_addc_u32 s39, s5, 0
	global_load_dwordx4 v[30:33], v66, s[38:39] nt
	s_add_u32 s35, s34, 0x10000
	s_min_u32 s35, s35, s33
	s_add_u32 s36, s4, s35
	s_addc_u32 s37, s5, 0
	global_load_dwordx4 v[34:37], v66, s[36:37] nt
	s_add_u32 s35, s34, 0x12000
	s_min_u32 s35, s35, s33
	s_add_u32 s38, s4, s35
	s_addc_u32 s39, s5, 0
	global_load_dwordx4 v[38:41], v66, s[38:39] nt
	s_add_u32 s35, s34, 0x14000
	s_min_u32 s35, s35, s33
	s_add_u32 s36, s4, s35
	s_addc_u32 s37, s5, 0
	global_load_dwordx4 v[42:45], v66, s[36:37] nt
	s_add_u32 s35, s34, 0x16000
	s_min_u32 s35, s35, s33
	s_add_u32 s38, s4, s35
	s_addc_u32 s39, s5, 0
	global_load_dwordx4 v[46:49], v66, s[38:39] nt
	s_add_u32 s35, s34, 0x18000
	s_min_u32 s35, s35, s33
	s_add_u32 s36, s4, s35
	s_addc_u32 s37, s5, 0
	global_load_dwordx4 v[50:53], v66, s[36:37] nt
	s_add_u32 s35, s34, 0x1a000
	s_min_u32 s35, s35, s33
	s_add_u32 s38, s4, s35
	s_addc_u32 s39, s5, 0
	global_load_dwordx4 v[54:57], v66, s[38:39] nt
	s_add_u32 s35, s34, 0x1c000
	s_min_u32 s35, s35, s33
	s_add_u32 s36, s4, s35
	s_addc_u32 s37, s5, 0
	global_load_dwordx4 v[58:61], v66, s[36:37] nt
	s_add_u32 s35, s34, 0x1e000
	s_min_u32 s35, s35, s33
	s_add_u32 s38, s4, s35
	s_addc_u32 s39, s5, 0
	global_load_dwordx4 v[62:65], v66, s[38:39] nt
	s_min_u32 s35, s34, s33
	s_add_u32 s36, s6, s35
	s_addc_u32 s37, s7, 0
	s_waitcnt vmcnt(15)
	global_store_dwordx4 v66, v[2:5], s[36:37] nt
	s_add_u32 s35, s34, 0x2000
	s_min_u32 s35, s35, s33
	s_add_u32 s38, s6, s35
	s_addc_u32 s39, s7, 0
	s_waitcnt vmcnt(15)
	global_store_dwordx4 v66, v[6:9], s[38:39] nt
	s_add_u32 s35, s34, 0x4000
	s_min_u32 s35, s35, s33
	s_add_u32 s36, s6, s35
	s_addc_u32 s37, s7, 0
	s_waitcnt vmcnt(15)
	global_store_dwordx4 v66, v[10:13], s[36:37] nt
	s_add_u32 s35, s34, 0x6000
	s_min_u32 s35, s35, s33
	s_add_u32 s38, s6, s35
	s_addc_u32 s39, s7, 0
	s_waitcnt vmcnt(15)
	global_store_dwordx4 v66, v[14:17], s[38:39] nt
	s_add_u32 s35, s34, 0x8000
	s_min_u32 s35, s35, s33
	s_add_u32 s36, s6, s35
	s_addc_u32 s37, s7, 0
	s_waitcnt vmcnt(15)
	global_store_dwordx4 v66, v[18:21], s[36:37] nt
	s_add_u32 s35, s34, 0xa000
	s_min_u32 s35, s35, s33
	s_add_u32 s38, s6, s35
	s_addc_u32 s39, s7, 0
	s_waitcnt vmcnt(15)
	global_store_dwordx4 v66, v[22:25], s[38:39] nt
	s_add_u32 s35, s34, 0xc000
	s_min_u32 s35, s35, s33
	s_add_u32 s36, s6, s35
	s_addc_u32 s37, s7, 0
	s_waitcnt vmcnt(15)
	global_store_dwordx4 v66, v[26:29], s[36:37] nt
	s_add_u32 s35, s34, 0xe000
	s_min_u32 s35, s35, s33
	s_add_u32 s38, s6, s35
	s_addc_u32 s39, s7, 0
	s_waitcnt vmcnt(15)
	global_store_dwordx4 v66, v[30:33], s[38:39] nt
	s_add_u32 s35, s34, 0x10000
	s_min_u32 s35, s35, s33
	s_add_u32 s36, s6, s35
	s_addc_u32 s37, s7, 0
	s_waitcnt vmcnt(15)
	global_store_dwordx4 v66, v[34:37], s[36:37] nt
	s_add_u32 s35, s34, 0x12000
	s_min_u32 s35, s35, s33
	s_add_u32 s38, s6, s35
	s_addc_u32 s39, s7, 0
	s_waitcnt vmcnt(15)
	global_store_dwordx4 v66, v[38:41], s[38:39] nt
	s_add_u32 s35, s34, 0x14000
	s_min_u32 s35, s35, s33
	s_add_u32 s36, s6, s35
	s_addc_u32 s37, s7, 0
	s_waitcnt vmcnt(15)
	global_store_dwordx4 v66, v[42:45], s[36:37] nt
	s_add_u32 s35, s34, 0x16000
	s_min_u32 s35, s35, s33
	s_add_u32 s38, s6, s35
	s_addc_u32 s39, s7, 0
	s_waitcnt vmcnt(15)
	global_store_dwordx4 v66, v[46:49], s[38:39] nt
	s_add_u32 s35, s34, 0x18000
	s_min_u32 s35, s35, s33
	s_add_u32 s36, s6, s35
	s_addc_u32 s37, s7, 0
	s_waitcnt vmcnt(15)
	global_store_dwordx4 v66, v[50:53], s[36:37] nt
	s_add_u32 s35, s34, 0x1a000
	s_min_u32 s35, s35, s33
	s_add_u32 s38, s6, s35
	s_addc_u32 s39, s7, 0
	s_waitcnt vmcnt(15)
	global_store_dwordx4 v66, v[54:57], s[38:39] nt
	s_add_u32 s35, s34, 0x1c000
	s_min_u32 s35, s35, s33
	s_add_u32 s36, s6, s35
	s_addc_u32 s37, s7, 0
	s_waitcnt vmcnt(15)
	global_store_dwordx4 v66, v[58:61], s[36:37] nt
	s_add_u32 s35, s34, 0x1e000
	s_min_u32 s35, s35, s33
	s_add_u32 s38, s6, s35
	s_addc_u32 s39, s7, 0
	s_waitcnt vmcnt(15)
	global_store_dwordx4 v66, v[62:65], s[38:39] nt
	s_add_u32 s2, s2, 1
	s_branch .Lfc8_loop
.Lfc8_done:
	s_branch .LBB0_1560

; #define LAS __attribute__((address_space(3)))
; __global__ void __launch_bounds__(512, 2) mk_fwd(Args args) {
;     extern __shared__ __attribute__((aligned(16))) unsigned char lds_raw[];
;     LAS unsigned char* lds = (LAS unsigned char*)lds_raw;
;     const int tid = threadIdx.x, G = gridDim.x, bid = blockIdx.x;
	.amdhsa_kernel _Z6mk_fwd4Args
		.amdhsa_group_segment_fixed_size 0
		.amdhsa_private_segment_fixed_size 0
		.amdhsa_kernarg_size 496
		.amdhsa_user_sgpr_count 2
		.amdhsa_user_sgpr_dispatch_ptr 0
		.amdhsa_user_sgpr_queue_ptr 0
		.amdhsa_user_sgpr_kernarg_segment_ptr 1
		.amdhsa_user_sgpr_dispatch_id 0
		.amdhsa_user_sgpr_kernarg_preload_length 0
		.amdhsa_user_sgpr_kernarg_preload_offset 0
		.amdhsa_user_sgpr_private_segment_size 0
		.amdhsa_uses_dynamic_stack 0
		.amdhsa_enable_private_segment 0
		.amdhsa_system_sgpr_workgroup_id_x 1
		.amdhsa_system_sgpr_workgroup_id_y 0
		.amdhsa_system_sgpr_workgroup_id_z 0
		.amdhsa_system_sgpr_workgroup_info 0
		.amdhsa_system_vgpr_workitem_id 0
		.amdhsa_next_free_vgpr 251
		.amdhsa_next_free_sgpr 102
		.amdhsa_accum_offset 252
		.amdhsa_reserve_vcc 1
		.amdhsa_float_round_mode_32 0
		.amdhsa_float_round_mode_16_64 0
		.amdhsa_float_denorm_mode_32 3
		.amdhsa_float_denorm_mode_16_64 3
		.amdhsa_dx10_clamp 1
		.amdhsa_ieee_mode 1
		.amdhsa_fp16_overflow 0
		.amdhsa_tg_split 0
		.amdhsa_exception_fp_ieee_invalid_op 0
		.amdhsa_exception_fp_denorm_src 0
		.amdhsa_exception_fp_ieee_div_zero 0
		.amdhsa_exception_fp_ieee_overflow 0
		.amdhsa_exception_fp_ieee_underflow 0
		.amdhsa_exception_fp_ieee_inexact 0
		.amdhsa_exception_int_div_zero 0
	.end_amdhsa_kernel

; __global__ void __launch_bounds__(512, 2) mk_fwd(Args args) {
amdhsa.kernels:
  - .agpr_count:     0
    .args:
      - .offset:         0
        .size:           240
        .value_kind:     by_value
      - .offset:         240
        .size:           4
        .value_kind:     hidden_block_count_x
      - .offset:         244
        .size:           4
        .value_kind:     hidden_block_count_y
      - .offset:         248
        .size:           4
        .value_kind:     hidden_block_count_z
      - .offset:         252
        .size:           2
        .value_kind:     hidden_group_size_x
      - .offset:         254
        .size:           2
        .value_kind:     hidden_group_size_y
      - .offset:         256
        .size:           2
        .value_kind:     hidden_group_size_z
      - .offset:         258
        .size:           2
        .value_kind:     hidden_remainder_x
      - .offset:         260
        .size:           2
        .value_kind:     hidden_remainder_y
      - .offset:         262
        .size:           2
        .value_kind:     hidden_remainder_z
      - .offset:         280
        .size:           8
        .value_kind:     hidden_global_offset_x
      - .offset:         288
        .size:           8
        .value_kind:     hidden_global_offset_y
      - .offset:         296
        .size:           8
        .value_kind:     hidden_global_offset_z
      - .offset:         304
        .size:           2
        .value_kind:     hidden_grid_dims
      - .offset:         360
        .size:           4
        .value_kind:     hidden_dynamic_lds_size
    .group_segment_fixed_size: 0
    .kernarg_segment_align: 8
    .kernarg_segment_size: 496
    .language:       OpenCL C
    .language_version:
      - 2
      - 0
    .max_flat_workgroup_size: 512
    .name:           _Z6mk_fwd4Args
    .private_segment_fixed_size: 0
    .sgpr_count:     108
    .sgpr_spill_count: 52
    .symbol:         _Z6mk_fwd4Args.kd
    .uniform_work_group_size: 1
    .uses_dynamic_stack: false
    .vgpr_count:     251
    .vgpr_spill_count: 0
    .wavefront_size: 64
